# v2 + XCD leader issues its L1 invalidate together with the L2 write-back instead of after the cross-XCD release
# baseline (speedup 1.0000x reference)
; __device__ __forceinline__ unsigned xb_add(unsigned* p, unsigned v) { return __hip_atomic_fetch_add(p, v, __ATOMIC_RELAXED, __HIP_MEMORY_SCOPE_AGENT); }
; __device__ __forceinline__ void xcd_barrier(const XcdBarrier& b) {
;     ...
;         if (old + 1u == (gen + 1u) * nloc) {
;             __builtin_amdgcn_fence(__ATOMIC_RELEASE, "agent");
;             asm volatile("s_waitcnt vmcnt(0)" ::: "memory");
;             const unsigned og = xb_add(&bar[XB_TOP], 1u);
;             const unsigned tg = og / nx;
;             if (og + 1u == (tg + 1u) * nx) xb_add(&bar[XB_TOPGEN], 1u);
.LBB0_125:
	s_andn2_saveexec_b64 s[8:9], s[8:9]
	s_cbranch_execz .LBB0_145
	s_mov_b64 s[8:9], exec
	buffer_wbl2 sc1
	buffer_inv sc1
	s_waitcnt lgkmcnt(0)
	s_waitcnt vmcnt(0)
	v_mbcnt_lo_u32_b32 v3, s8, 0
	v_mbcnt_hi_u32_b32 v3, s9, v3
	v_cmp_eq_u32_e32 vcc, 0, v3
	s_and_saveexec_b64 s[10:11], vcc
	s_cbranch_execz .LBB0_128
	s_bcnt1_i32_b64 s8, s[8:9]
	v_mov_b32_e32 v4, 0x7000
	v_mov_b32_e32 v5, s8
	global_atomic_add v4, v4, v5, s[88:89] offset:1024 sc0

; __device__ __forceinline__ unsigned xb_add(unsigned* p, unsigned v) { return __hip_atomic_fetch_add(p, v, __ATOMIC_RELAXED, __HIP_MEMORY_SCOPE_AGENT); }
; __device__ __forceinline__ void xcd_barrier(const XcdBarrier& b) {
;     ...
;             __builtin_amdgcn_fence(__ATOMIC_ACQUIRE, "agent");
;             xb_add(&bar[XB_XGEN(b.x)], 1u);
;             asm volatile("s_waitcnt vmcnt(0)" ::: "memory");
.LBB0_142:
	s_or_b64 exec, exec, s[8:9]
	s_mov_b64 s[8:9], exec
	v_mbcnt_lo_u32_b32 v2, s8, 0
	v_mbcnt_hi_u32_b32 v2, s9, v2
	v_cmp_eq_u32_e32 vcc, 0, v2
	s_waitcnt vmcnt(0)
	s_and_saveexec_b64 s[10:11], vcc
	s_cbranch_execz .LBB0_144
	s_bcnt1_i32_b64 s8, s[8:9]
	v_mov_b32_e32 v2, 0x2000
	v_mov_b32_e32 v3, s8
	global_atomic_add v2, v3, s[4:5] offset:1024

; __device__ __forceinline__ unsigned xb_add(unsigned* p, unsigned v) { return __hip_atomic_fetch_add(p, v, __ATOMIC_RELAXED, __HIP_MEMORY_SCOPE_AGENT); }
; __device__ __forceinline__ void xcd_barrier(const XcdBarrier& b) {
;     ...
;         if (old + 1u == (gen + 1u) * nloc) {
;             __builtin_amdgcn_fence(__ATOMIC_RELEASE, "agent");
;             asm volatile("s_waitcnt vmcnt(0)" ::: "memory");
;             const unsigned og = xb_add(&bar[XB_TOP], 1u);
;             const unsigned tg = og / nx;
;             if (og + 1u == (tg + 1u) * nx) xb_add(&bar[XB_TOPGEN], 1u);
.LBB0_188:
	s_andn2_saveexec_b64 s[6:7], s[6:7]
	s_cbranch_execz .LBB0_208
	s_mov_b64 s[6:7], exec
	buffer_wbl2 sc1
	buffer_inv sc1
	s_waitcnt lgkmcnt(0)
	s_waitcnt vmcnt(0)
	v_mbcnt_lo_u32_b32 v3, s6, 0
	v_mbcnt_hi_u32_b32 v3, s7, v3
	v_cmp_eq_u32_e32 vcc, 0, v3
	s_and_saveexec_b64 s[8:9], vcc
	s_cbranch_execz .LBB0_191
	s_bcnt1_i32_b64 s6, s[6:7]
	v_mov_b32_e32 v4, 0x7000
	v_mov_b32_e32 v5, s6
	global_atomic_add v4, v4, v5, s[88:89] offset:1024 sc0

; __device__ __forceinline__ unsigned xb_add(unsigned* p, unsigned v) { return __hip_atomic_fetch_add(p, v, __ATOMIC_RELAXED, __HIP_MEMORY_SCOPE_AGENT); }
; __device__ __forceinline__ void xcd_barrier(const XcdBarrier& b) {
;     ...
;             __builtin_amdgcn_fence(__ATOMIC_ACQUIRE, "agent");
;             xb_add(&bar[XB_XGEN(b.x)], 1u);
;             asm volatile("s_waitcnt vmcnt(0)" ::: "memory");
.LBB0_205:
	s_or_b64 exec, exec, s[6:7]
	s_mov_b64 s[6:7], exec
	v_mbcnt_lo_u32_b32 v2, s6, 0
	v_mbcnt_hi_u32_b32 v2, s7, v2
	v_cmp_eq_u32_e32 vcc, 0, v2
	s_waitcnt vmcnt(0)
	s_and_saveexec_b64 s[8:9], vcc
	s_cbranch_execz .LBB0_207
	s_bcnt1_i32_b64 s6, s[6:7]
	v_mov_b32_e32 v2, 0x2000
	v_mov_b32_e32 v3, s6
	global_atomic_add v2, v3, s[4:5] offset:1024

; __device__ __forceinline__ unsigned xb_add(unsigned* p, unsigned v) { return __hip_atomic_fetch_add(p, v, __ATOMIC_RELAXED, __HIP_MEMORY_SCOPE_AGENT); }
; __device__ __forceinline__ void xcd_barrier(const XcdBarrier& b) {
;     ...
;         if (old + 1u == (gen + 1u) * nloc) {
;             __builtin_amdgcn_fence(__ATOMIC_RELEASE, "agent");
;             asm volatile("s_waitcnt vmcnt(0)" ::: "memory");
;             const unsigned og = xb_add(&bar[XB_TOP], 1u);
;             const unsigned tg = og / nx;
;             if (og + 1u == (tg + 1u) * nx) xb_add(&bar[XB_TOPGEN], 1u);
.LBB0_2402:
	s_andn2_saveexec_b64 s[6:7], s[6:7]
	s_cbranch_execz .LBB0_2422
	s_mov_b64 s[6:7], exec
	buffer_wbl2 sc1
	buffer_inv sc1
	s_waitcnt lgkmcnt(0)
	s_waitcnt vmcnt(0)
	v_mbcnt_lo_u32_b32 v2, s6, 0
	v_mbcnt_hi_u32_b32 v2, s7, v2
	v_cmp_eq_u32_e32 vcc, 0, v2
	s_and_saveexec_b64 s[8:9], vcc
	s_cbranch_execz .LBB0_2405
	s_bcnt1_i32_b64 s6, s[6:7]
	v_mov_b32_e32 v3, 0x7000
	v_mov_b32_e32 v4, s6
	global_atomic_add v3, v3, v4, s[88:89] offset:1024 sc0

; __device__ __forceinline__ unsigned xb_add(unsigned* p, unsigned v) { return __hip_atomic_fetch_add(p, v, __ATOMIC_RELAXED, __HIP_MEMORY_SCOPE_AGENT); }
; __device__ __forceinline__ void xcd_barrier(const XcdBarrier& b) {
;     ...
;             __builtin_amdgcn_fence(__ATOMIC_ACQUIRE, "agent");
;             xb_add(&bar[XB_XGEN(b.x)], 1u);
;             asm volatile("s_waitcnt vmcnt(0)" ::: "memory");
.LBB0_2419:
	s_or_b64 exec, exec, s[6:7]
	s_mov_b64 s[6:7], exec
	v_mbcnt_lo_u32_b32 v1, s6, 0
	v_mbcnt_hi_u32_b32 v1, s7, v1
	v_cmp_eq_u32_e32 vcc, 0, v1
	s_waitcnt vmcnt(0)
	s_and_saveexec_b64 s[8:9], vcc
	s_cbranch_execz .LBB0_2421
	s_bcnt1_i32_b64 s6, s[6:7]
	v_mov_b32_e32 v1, 0x2000
	v_mov_b32_e32 v2, s6
	global_atomic_add v1, v2, s[4:5] offset:1024

; __device__ __forceinline__ unsigned xb_add(unsigned* p, unsigned v) { return __hip_atomic_fetch_add(p, v, __ATOMIC_RELAXED, __HIP_MEMORY_SCOPE_AGENT); }
; __device__ __forceinline__ void xcd_barrier(const XcdBarrier& b) {
;     ...
;         if (old + 1u == (gen + 1u) * nloc) {
;             __builtin_amdgcn_fence(__ATOMIC_RELEASE, "agent");
;             asm volatile("s_waitcnt vmcnt(0)" ::: "memory");
;             const unsigned og = xb_add(&bar[XB_TOP], 1u);
;             const unsigned tg = og / nx;
;             if (og + 1u == (tg + 1u) * nx) xb_add(&bar[XB_TOPGEN], 1u);
.LBB0_2559:
	s_andn2_saveexec_b64 s[4:5], s[4:5]
	s_cbranch_execz .LBB0_2579
	s_mov_b64 s[4:5], exec
	buffer_wbl2 sc1
	buffer_inv sc1
	s_waitcnt lgkmcnt(0)
	s_waitcnt vmcnt(0)
	v_mbcnt_lo_u32_b32 v1, s4, 0
	v_mbcnt_hi_u32_b32 v1, s5, v1
	v_cmp_eq_u32_e32 vcc, 0, v1
	s_and_saveexec_b64 s[6:7], vcc
	s_cbranch_execz .LBB0_2562
	s_bcnt1_i32_b64 s4, s[4:5]
	v_mov_b32_e32 v2, 0x7000
	v_mov_b32_e32 v3, s4
	global_atomic_add v2, v2, v3, s[88:89] offset:1024 sc0

; __device__ __forceinline__ unsigned xb_add(unsigned* p, unsigned v) { return __hip_atomic_fetch_add(p, v, __ATOMIC_RELAXED, __HIP_MEMORY_SCOPE_AGENT); }
; __device__ __forceinline__ void xcd_barrier(const XcdBarrier& b) {
;     ...
;             __builtin_amdgcn_fence(__ATOMIC_ACQUIRE, "agent");
;             xb_add(&bar[XB_XGEN(b.x)], 1u);
;             asm volatile("s_waitcnt vmcnt(0)" ::: "memory");
.LBB0_2576:
	s_or_b64 exec, exec, s[4:5]
	s_mov_b64 s[4:5], exec
	v_mbcnt_lo_u32_b32 v0, s4, 0
	v_mbcnt_hi_u32_b32 v0, s5, v0
	v_cmp_eq_u32_e32 vcc, 0, v0
	s_waitcnt vmcnt(0)
	s_and_saveexec_b64 s[6:7], vcc
	s_cbranch_execz .LBB0_2578
	s_bcnt1_i32_b64 s4, s[4:5]
	v_mov_b32_e32 v0, 0x2000
	v_mov_b32_e32 v1, s4
	global_atomic_add v0, v1, s[2:3] offset:1024
